# GEMM K-loops: LDS-DMA loads use SGPR base + 32-bit VGPR offset form (no 64-bit VALU add per load), duplicate lgkmcnt(0) after barrier dropped; on top of conv prefetch + P7
# speedup vs baseline: 1.0144x; 1.0094x over previous
.LBB0_90:
	ds_read_b128 v[150:153], v159
	ds_read_b128 v[174:177], v160
	ds_read_b128 v[178:181], v161
	ds_read_b128 v[182:185], v162
	ds_read_b128 v[186:189], v163
	ds_read_b128 v[190:193], v164
	ds_read_b128 v[194:197], v165
	ds_read_b128 v[198:201], v166
	s_add_u32 s30, s28, 0xfff00080
	s_addc_u32 s31, s29, -1
	s_cmp_eq_u32 s60, 60
	s_cselect_b32 s37, s9, s31
	s_cselect_b32 s36, s11, s30
	s_cselect_b32 s31, s21, s59
	s_cselect_b32 s30, s23, s58
	s_add_i32 m0, s42, 0xc000
	ds_read_b128 v[202:205], v167
	ds_read_b128 v[206:209], v167 offset:2048
	ds_read_b128 v[210:213], v168
	ds_read_b128 v[214:217], v168 offset:2048
	ds_read_b128 v[218:221], v167 offset:4096
	ds_read_b128 v[222:225], v167 offset:6144
	ds_read_b128 v[226:229], v168 offset:4096
	ds_read_b128 v[230:233], v168 offset:6144
	global_load_lds_dwordx4 v142, s[28:29]
	s_add_i32 m0, s42, 0xe000
	s_nop 0
	global_load_lds_dwordx4 v144, s[28:29]
	s_waitcnt vmcnt(8)
	s_waitcnt lgkmcnt(0)
	s_barrier
	s_setprio 1
	v_mfma_f32_16x16x32_bf16 v[126:129], v[150:153], v[202:205], v[126:129]
	v_mfma_f32_16x16x32_bf16 v[122:125], v[178:181], v[202:205], v[122:125]
	v_mfma_f32_16x16x32_bf16 v[110:113], v[150:153], v[206:209], v[110:113]
	v_mfma_f32_16x16x32_bf16 v[106:109], v[178:181], v[206:209], v[106:109]
	v_mfma_f32_16x16x32_bf16 v[94:97], v[150:153], v[218:221], v[94:97]
	v_mfma_f32_16x16x32_bf16 v[90:93], v[178:181], v[218:221], v[90:93]
	v_mfma_f32_16x16x32_bf16 v[78:81], v[150:153], v[222:225], v[78:81]
	v_mfma_f32_16x16x32_bf16 v[74:77], v[178:181], v[222:225], v[74:77]
	v_mfma_f32_16x16x32_bf16 v[126:129], v[174:177], v[210:213], v[126:129]
	v_mfma_f32_16x16x32_bf16 v[122:125], v[182:185], v[210:213], v[122:125]
	v_mfma_f32_16x16x32_bf16 v[110:113], v[174:177], v[214:217], v[110:113]
	v_mfma_f32_16x16x32_bf16 v[106:109], v[182:185], v[214:217], v[106:109]
	v_mfma_f32_16x16x32_bf16 v[94:97], v[174:177], v[226:229], v[94:97]
	v_mfma_f32_16x16x32_bf16 v[90:93], v[182:185], v[226:229], v[90:93]
	v_mfma_f32_16x16x32_bf16 v[78:81], v[174:177], v[230:233], v[78:81]
	v_mfma_f32_16x16x32_bf16 v[74:77], v[182:185], v[230:233], v[74:77]
	s_setprio 0
	s_setprio 1
	v_mfma_f32_16x16x32_bf16 v[118:121], v[186:189], v[202:205], v[118:121]
	v_mfma_f32_16x16x32_bf16 v[114:117], v[194:197], v[202:205], v[114:117]
	v_mfma_f32_16x16x32_bf16 v[102:105], v[186:189], v[206:209], v[102:105]
	v_mfma_f32_16x16x32_bf16 v[98:101], v[194:197], v[206:209], v[98:101]
	v_mfma_f32_16x16x32_bf16 v[86:89], v[186:189], v[218:221], v[86:89]
	v_mfma_f32_16x16x32_bf16 v[82:85], v[194:197], v[218:221], v[82:85]
	v_mfma_f32_16x16x32_bf16 v[70:73], v[186:189], v[222:225], v[70:73]
	v_mfma_f32_16x16x32_bf16 v[66:69], v[194:197], v[222:225], v[66:69]
	v_mfma_f32_16x16x32_bf16 v[118:121], v[190:193], v[210:213], v[118:121]
	v_mfma_f32_16x16x32_bf16 v[114:117], v[198:201], v[210:213], v[114:117]
	v_mfma_f32_16x16x32_bf16 v[102:105], v[190:193], v[214:217], v[102:105]
	v_mfma_f32_16x16x32_bf16 v[98:101], v[198:201], v[214:217], v[98:101]
	v_mfma_f32_16x16x32_bf16 v[86:89], v[190:193], v[226:229], v[86:89]
	v_mfma_f32_16x16x32_bf16 v[82:85], v[198:201], v[226:229], v[82:85]
	v_mfma_f32_16x16x32_bf16 v[70:73], v[190:193], v[230:233], v[70:73]
	v_mfma_f32_16x16x32_bf16 v[66:69], v[198:201], v[230:233], v[66:69]
	s_setprio 0
	s_barrier
	s_add_i32 s61, s56, s41
	s_mov_b32 m0, s61
	ds_read_b128 v[202:205], v167 offset:16384
	ds_read_b128 v[206:209], v167 offset:18432
	ds_read_b128 v[210:213], v168 offset:16384
	ds_read_b128 v[214:217], v168 offset:18432
	ds_read_b128 v[218:221], v167 offset:20480
	ds_read_b128 v[222:225], v167 offset:22528
	ds_read_b128 v[226:229], v168 offset:20480
	ds_read_b128 v[230:233], v168 offset:22528
	global_load_lds_dwordx4 v132, s[30:31]
	s_add_i32 m0, s61, 0x2000
	s_add_u32 s62, s30, 0x4000
	s_addc_u32 s63, s31, 0
	s_add_i32 s61, s57, s41
	global_load_lds_dwordx4 v136, s[30:31]
	s_mov_b32 m0, s61
	v_lshl_add_u64 v[234:235], s[36:37], 0, v[134:135]
	global_load_lds_dwordx4 v132, s[62:63]
	s_add_i32 m0, s61, 0x2000
	s_nop 0
	global_load_lds_dwordx4 v136, s[62:63]
	v_lshl_add_u64 v[154:155], s[36:37], 0, v[130:131]
	s_mov_b32 m0, s42
	s_nop 0
	global_load_lds_dwordx4 v[154:155], off
	s_mov_b32 m0, s43
	s_nop 0
	global_load_lds_dwordx4 v[234:235], off
	s_waitcnt vmcnt(8)
	s_waitcnt lgkmcnt(0)
	s_barrier
	s_setprio 1
	v_mfma_f32_16x16x32_bf16 v[62:65], v[150:153], v[202:205], v[62:65]
	v_mfma_f32_16x16x32_bf16 v[58:61], v[178:181], v[202:205], v[58:61]
	v_mfma_f32_16x16x32_bf16 v[46:49], v[150:153], v[206:209], v[46:49]
	v_mfma_f32_16x16x32_bf16 v[42:45], v[178:181], v[206:209], v[42:45]
	v_mfma_f32_16x16x32_bf16 v[30:33], v[150:153], v[218:221], v[30:33]
	v_mfma_f32_16x16x32_bf16 v[26:29], v[178:181], v[218:221], v[26:29]
	v_mfma_f32_16x16x32_bf16 v[14:17], v[150:153], v[222:225], v[14:17]
	v_mfma_f32_16x16x32_bf16 v[10:13], v[178:181], v[222:225], v[10:13]
	v_mfma_f32_16x16x32_bf16 v[62:65], v[174:177], v[210:213], v[62:65]
	v_mfma_f32_16x16x32_bf16 v[58:61], v[182:185], v[210:213], v[58:61]
	v_mfma_f32_16x16x32_bf16 v[46:49], v[174:177], v[214:217], v[46:49]
	v_mfma_f32_16x16x32_bf16 v[42:45], v[182:185], v[214:217], v[42:45]
	v_mfma_f32_16x16x32_bf16 v[30:33], v[174:177], v[226:229], v[30:33]
	v_mfma_f32_16x16x32_bf16 v[26:29], v[182:185], v[226:229], v[26:29]
	v_mfma_f32_16x16x32_bf16 v[14:17], v[174:177], v[230:233], v[14:17]
	v_mfma_f32_16x16x32_bf16 v[10:13], v[182:185], v[230:233], v[10:13]
	s_setprio 0
	s_setprio 1
	v_mfma_f32_16x16x32_bf16 v[54:57], v[186:189], v[202:205], v[54:57]
	v_mfma_f32_16x16x32_bf16 v[50:53], v[194:197], v[202:205], v[50:53]
	v_mfma_f32_16x16x32_bf16 v[38:41], v[186:189], v[206:209], v[38:41]
	v_mfma_f32_16x16x32_bf16 v[34:37], v[194:197], v[206:209], v[34:37]
	v_mfma_f32_16x16x32_bf16 v[22:25], v[186:189], v[218:221], v[22:25]
	v_mfma_f32_16x16x32_bf16 v[18:21], v[194:197], v[218:221], v[18:21]
	v_mfma_f32_16x16x32_bf16 v[6:9], v[186:189], v[222:225], v[6:9]
	v_mfma_f32_16x16x32_bf16 v[2:5], v[194:197], v[222:225], v[2:5]
	v_mfma_f32_16x16x32_bf16 v[54:57], v[190:193], v[210:213], v[54:57]
	v_mfma_f32_16x16x32_bf16 v[50:53], v[198:201], v[210:213], v[50:53]
	v_mfma_f32_16x16x32_bf16 v[38:41], v[190:193], v[214:217], v[38:41]
	v_mfma_f32_16x16x32_bf16 v[34:37], v[198:201], v[214:217], v[34:37]
	v_mfma_f32_16x16x32_bf16 v[22:25], v[190:193], v[226:229], v[22:25]
	v_mfma_f32_16x16x32_bf16 v[18:21], v[198:201], v[226:229], v[18:21]
	v_mfma_f32_16x16x32_bf16 v[6:9], v[190:193], v[230:233], v[6:9]
	v_mfma_f32_16x16x32_bf16 v[2:5], v[198:201], v[230:233], v[2:5]
	s_setprio 0
	s_barrier
	s_add_i32 s61, 0, 0x18000
	v_add_u32_e32 v138, s61, v156
	v_add_u32_e32 v174, s61, v157
	s_add_i32 s62, 0, 0x1c000
	ds_read_b128 v[150:153], v138
	ds_read_b128 v[174:177], v174
	ds_read_b128 v[178:181], v169
	ds_read_b128 v[182:185], v170
	v_add_u32_e32 v138, s62, v156
	v_add_u32_e32 v190, s62, v157
	ds_read_b128 v[186:189], v138
	ds_read_b128 v[190:193], v190
	ds_read_b128 v[194:197], v171
	ds_read_b128 v[198:201], v172
	s_add_u32 s36, s36, 0x100000
	s_addc_u32 s37, s37, 0
	s_mov_b32 m0, s44
	ds_read_b128 v[202:205], v167 offset:32768
	ds_read_b128 v[206:209], v167 offset:34816
	ds_read_b128 v[210:213], v168 offset:32768
	ds_read_b128 v[214:217], v168 offset:34816
	ds_read_b128 v[218:221], v167 offset:36864
	ds_read_b128 v[222:225], v167 offset:38912
	ds_read_b128 v[226:229], v168 offset:36864
	ds_read_b128 v[230:233], v168 offset:38912
	global_load_lds_dwordx4 v130, s[36:37]
	s_mov_b32 m0, s45
	s_nop 0
	global_load_lds_dwordx4 v134, s[36:37]
	s_waitcnt vmcnt(8)
	s_waitcnt lgkmcnt(0)
	s_barrier
	s_setprio 1
	v_mfma_f32_16x16x32_bf16 v[126:129], v[150:153], v[202:205], v[126:129]
	v_mfma_f32_16x16x32_bf16 v[122:125], v[178:181], v[202:205], v[122:125]
	v_mfma_f32_16x16x32_bf16 v[110:113], v[150:153], v[206:209], v[110:113]
	v_mfma_f32_16x16x32_bf16 v[106:109], v[178:181], v[206:209], v[106:109]
	v_mfma_f32_16x16x32_bf16 v[94:97], v[150:153], v[218:221], v[94:97]
	v_mfma_f32_16x16x32_bf16 v[90:93], v[178:181], v[218:221], v[90:93]
	v_mfma_f32_16x16x32_bf16 v[78:81], v[150:153], v[222:225], v[78:81]
	v_mfma_f32_16x16x32_bf16 v[74:77], v[178:181], v[222:225], v[74:77]
	v_mfma_f32_16x16x32_bf16 v[126:129], v[174:177], v[210:213], v[126:129]
	v_mfma_f32_16x16x32_bf16 v[122:125], v[182:185], v[210:213], v[122:125]
	v_mfma_f32_16x16x32_bf16 v[110:113], v[174:177], v[214:217], v[110:113]
	v_mfma_f32_16x16x32_bf16 v[106:109], v[182:185], v[214:217], v[106:109]
	v_mfma_f32_16x16x32_bf16 v[94:97], v[174:177], v[226:229], v[94:97]
	v_mfma_f32_16x16x32_bf16 v[90:93], v[182:185], v[226:229], v[90:93]
	v_mfma_f32_16x16x32_bf16 v[78:81], v[174:177], v[230:233], v[78:81]
	v_mfma_f32_16x16x32_bf16 v[74:77], v[182:185], v[230:233], v[74:77]
	s_setprio 0
	s_setprio 1
	v_mfma_f32_16x16x32_bf16 v[118:121], v[186:189], v[202:205], v[118:121]
	v_mfma_f32_16x16x32_bf16 v[114:117], v[194:197], v[202:205], v[114:117]
	v_mfma_f32_16x16x32_bf16 v[102:105], v[186:189], v[206:209], v[102:105]
	v_mfma_f32_16x16x32_bf16 v[98:101], v[194:197], v[206:209], v[98:101]
	v_mfma_f32_16x16x32_bf16 v[86:89], v[186:189], v[218:221], v[86:89]
	v_mfma_f32_16x16x32_bf16 v[82:85], v[194:197], v[218:221], v[82:85]
	v_mfma_f32_16x16x32_bf16 v[70:73], v[186:189], v[222:225], v[70:73]
	v_mfma_f32_16x16x32_bf16 v[66:69], v[194:197], v[222:225], v[66:69]
	v_mfma_f32_16x16x32_bf16 v[118:121], v[190:193], v[210:213], v[118:121]
	v_mfma_f32_16x16x32_bf16 v[114:117], v[198:201], v[210:213], v[114:117]
	v_mfma_f32_16x16x32_bf16 v[102:105], v[190:193], v[214:217], v[102:105]
	v_mfma_f32_16x16x32_bf16 v[98:101], v[198:201], v[214:217], v[98:101]
	v_mfma_f32_16x16x32_bf16 v[86:89], v[190:193], v[226:229], v[86:89]
	v_mfma_f32_16x16x32_bf16 v[82:85], v[198:201], v[226:229], v[82:85]
	v_mfma_f32_16x16x32_bf16 v[70:73], v[190:193], v[230:233], v[70:73]
	v_mfma_f32_16x16x32_bf16 v[66:69], v[198:201], v[230:233], v[66:69]
	s_setprio 0
	s_barrier
	s_add_u32 s36, s30, 0x8000
	s_addc_u32 s37, s31, 0
	s_add_i32 s61, s61, s41
	s_mov_b32 m0, s61
	ds_read_b128 v[202:205], v167 offset:49152
	ds_read_b128 v[206:209], v167 offset:51200
	ds_read_b128 v[210:213], v168 offset:49152
	ds_read_b128 v[214:217], v168 offset:51200
	ds_read_b128 v[218:221], v167 offset:53248
	ds_read_b128 v[222:225], v167 offset:55296
	ds_read_b128 v[226:229], v168 offset:53248
	ds_read_b128 v[230:233], v168 offset:55296
	global_load_lds_dwordx4 v132, s[36:37]
	s_add_i32 m0, s61, 0x2000
	s_add_u32 s30, s30, 0xc000
	v_lshl_add_u64 v[236:237], s[36:37], 0, v[136:137]
	s_addc_u32 s31, s31, 0
	s_add_i32 s36, s62, s41
	global_load_lds_dwordx4 v[236:237], off
	s_mov_b32 m0, s36
	v_lshl_add_u64 v[154:155], v[154:155], 0, s[14:15]
	global_load_lds_dwordx4 v132, s[30:31]
	s_add_i32 m0, s36, 0x2000
	s_nop 0
	global_load_lds_dwordx4 v136, s[30:31]
	s_mov_b32 m0, s51
	s_nop 0
	global_load_lds_dwordx4 v[154:155], off
	v_lshl_add_u64 v[154:155], v[234:235], 0, s[14:15]
	s_mov_b32 m0, s52
	s_nop 0
	global_load_lds_dwordx4 v[154:155], off
	s_waitcnt vmcnt(8)
	s_waitcnt lgkmcnt(0)
	s_barrier
	s_setprio 1
	v_mfma_f32_16x16x32_bf16 v[62:65], v[150:153], v[202:205], v[62:65]
	v_mfma_f32_16x16x32_bf16 v[58:61], v[178:181], v[202:205], v[58:61]
	v_mfma_f32_16x16x32_bf16 v[46:49], v[150:153], v[206:209], v[46:49]
	v_mfma_f32_16x16x32_bf16 v[42:45], v[178:181], v[206:209], v[42:45]
	v_mfma_f32_16x16x32_bf16 v[30:33], v[150:153], v[218:221], v[30:33]
	v_mfma_f32_16x16x32_bf16 v[26:29], v[178:181], v[218:221], v[26:29]
	v_mfma_f32_16x16x32_bf16 v[14:17], v[150:153], v[222:225], v[14:17]
	v_mfma_f32_16x16x32_bf16 v[10:13], v[178:181], v[222:225], v[10:13]
	v_mfma_f32_16x16x32_bf16 v[62:65], v[174:177], v[210:213], v[62:65]
	v_mfma_f32_16x16x32_bf16 v[58:61], v[182:185], v[210:213], v[58:61]
	v_mfma_f32_16x16x32_bf16 v[46:49], v[174:177], v[214:217], v[46:49]
	v_mfma_f32_16x16x32_bf16 v[42:45], v[182:185], v[214:217], v[42:45]
	v_mfma_f32_16x16x32_bf16 v[30:33], v[174:177], v[226:229], v[30:33]
	v_mfma_f32_16x16x32_bf16 v[26:29], v[182:185], v[226:229], v[26:29]
	v_mfma_f32_16x16x32_bf16 v[14:17], v[174:177], v[230:233], v[14:17]
	v_mfma_f32_16x16x32_bf16 v[10:13], v[182:185], v[230:233], v[10:13]
	s_setprio 0
	s_setprio 1
	v_mfma_f32_16x16x32_bf16 v[54:57], v[186:189], v[202:205], v[54:57]
	v_mfma_f32_16x16x32_bf16 v[50:53], v[194:197], v[202:205], v[50:53]
	v_mfma_f32_16x16x32_bf16 v[38:41], v[186:189], v[206:209], v[38:41]
	v_mfma_f32_16x16x32_bf16 v[34:37], v[194:197], v[206:209], v[34:37]
	v_mfma_f32_16x16x32_bf16 v[22:25], v[186:189], v[218:221], v[22:25]
	v_mfma_f32_16x16x32_bf16 v[18:21], v[194:197], v[218:221], v[18:21]
	v_mfma_f32_16x16x32_bf16 v[6:9], v[186:189], v[222:225], v[6:9]
	v_mfma_f32_16x16x32_bf16 v[2:5], v[194:197], v[222:225], v[2:5]
	v_mfma_f32_16x16x32_bf16 v[54:57], v[190:193], v[210:213], v[54:57]
	v_mfma_f32_16x16x32_bf16 v[50:53], v[198:201], v[210:213], v[50:53]
	v_mfma_f32_16x16x32_bf16 v[38:41], v[190:193], v[214:217], v[38:41]
	v_mfma_f32_16x16x32_bf16 v[34:37], v[198:201], v[214:217], v[34:37]
	v_mfma_f32_16x16x32_bf16 v[22:25], v[190:193], v[226:229], v[22:25]
	v_mfma_f32_16x16x32_bf16 v[18:21], v[198:201], v[226:229], v[18:21]
	v_mfma_f32_16x16x32_bf16 v[6:9], v[190:193], v[230:233], v[6:9]
	v_mfma_f32_16x16x32_bf16 v[2:5], v[198:201], v[230:233], v[2:5]
	s_setprio 0
	s_barrier
	s_add_i32 s60, s60, 2
	s_add_u32 s58, s58, 0x10000
	s_addc_u32 s59, s59, 0
	s_add_u32 s28, s28, 0x100
	s_addc_u32 s29, s29, 0
	s_cmp_gt_u32 s60, 61
	s_cbranch_scc0 .LBB0_90
	s_and_b64 vcc, exec, s[16:17]
	s_cbranch_vccz .LBB0_93
	s_barrier

.LBB0_495:
	ds_read_b128 v[58:61], v173
	ds_read_b128 v[70:73], v174
	ds_read_b128 v[74:77], v175
	ds_read_b128 v[78:81], v176
	ds_read_b128 v[164:167], v177
	ds_read_b128 v[188:191], v178
	ds_read_b128 v[192:195], v179
	ds_read_b128 v[196:199], v180
	s_add_u32 s56, s54, 0xfff00080
	s_addc_u32 s57, s55, -1
	s_cmp_eq_u32 s74, 60
	s_cselect_b32 s59, s29, s57
	s_cselect_b32 s58, s39, s56
	s_cselect_b32 s57, s27, s73
	s_cselect_b32 s56, s53, s72
	s_add_i32 m0, s42, 0xc000
	ds_read_b128 v[200:203], v181
	ds_read_b128 v[204:207], v181 offset:2048
	ds_read_b128 v[208:211], v182
	ds_read_b128 v[212:215], v182 offset:2048
	ds_read_b128 v[216:219], v181 offset:4096
	ds_read_b128 v[220:223], v181 offset:6144
	ds_read_b128 v[224:227], v182 offset:4096
	ds_read_b128 v[228:231], v182 offset:6144
	global_load_lds_dwordx4 v156, s[54:55]
	s_add_i32 m0, s42, 0xe000
	s_nop 0
	global_load_lds_dwordx4 v158, s[54:55]
	s_waitcnt vmcnt(8)
	s_waitcnt lgkmcnt(0)
	s_barrier
	s_setprio 1
	v_mfma_f32_16x16x32_bf16 v[142:145], v[58:61], v[200:203], v[142:145]
	v_mfma_f32_16x16x32_bf16 v[138:141], v[74:77], v[200:203], v[138:141]
	v_mfma_f32_16x16x32_bf16 v[126:129], v[58:61], v[204:207], v[126:129]
	v_mfma_f32_16x16x32_bf16 v[122:125], v[74:77], v[204:207], v[122:125]
	v_mfma_f32_16x16x32_bf16 v[110:113], v[58:61], v[216:219], v[110:113]
	v_mfma_f32_16x16x32_bf16 v[106:109], v[74:77], v[216:219], v[106:109]
	v_mfma_f32_16x16x32_bf16 v[94:97], v[58:61], v[220:223], v[94:97]
	v_mfma_f32_16x16x32_bf16 v[90:93], v[74:77], v[220:223], v[90:93]
	v_mfma_f32_16x16x32_bf16 v[142:145], v[70:73], v[208:211], v[142:145]
	v_mfma_f32_16x16x32_bf16 v[138:141], v[78:81], v[208:211], v[138:141]
	v_mfma_f32_16x16x32_bf16 v[126:129], v[70:73], v[212:215], v[126:129]
	v_mfma_f32_16x16x32_bf16 v[122:125], v[78:81], v[212:215], v[122:125]
	v_mfma_f32_16x16x32_bf16 v[110:113], v[70:73], v[224:227], v[110:113]
	v_mfma_f32_16x16x32_bf16 v[106:109], v[78:81], v[224:227], v[106:109]
	v_mfma_f32_16x16x32_bf16 v[94:97], v[70:73], v[228:231], v[94:97]
	v_mfma_f32_16x16x32_bf16 v[90:93], v[78:81], v[228:231], v[90:93]
	s_setprio 0
	s_setprio 1
	v_mfma_f32_16x16x32_bf16 v[134:137], v[164:167], v[200:203], v[134:137]
	v_mfma_f32_16x16x32_bf16 v[130:133], v[192:195], v[200:203], v[130:133]
	v_mfma_f32_16x16x32_bf16 v[118:121], v[164:167], v[204:207], v[118:121]
	v_mfma_f32_16x16x32_bf16 v[114:117], v[192:195], v[204:207], v[114:117]
	v_mfma_f32_16x16x32_bf16 v[102:105], v[164:167], v[216:219], v[102:105]
	v_mfma_f32_16x16x32_bf16 v[98:101], v[192:195], v[216:219], v[98:101]
	v_mfma_f32_16x16x32_bf16 v[86:89], v[164:167], v[220:223], v[86:89]
	v_mfma_f32_16x16x32_bf16 v[82:85], v[192:195], v[220:223], v[82:85]
	v_mfma_f32_16x16x32_bf16 v[134:137], v[188:191], v[208:211], v[134:137]
	v_mfma_f32_16x16x32_bf16 v[130:133], v[196:199], v[208:211], v[130:133]
	v_mfma_f32_16x16x32_bf16 v[118:121], v[188:191], v[212:215], v[118:121]
	v_mfma_f32_16x16x32_bf16 v[114:117], v[196:199], v[212:215], v[114:117]
	v_mfma_f32_16x16x32_bf16 v[102:105], v[188:191], v[224:227], v[102:105]
	v_mfma_f32_16x16x32_bf16 v[98:101], v[196:199], v[224:227], v[98:101]
	v_mfma_f32_16x16x32_bf16 v[86:89], v[188:191], v[228:231], v[86:89]
	v_mfma_f32_16x16x32_bf16 v[82:85], v[196:199], v[228:231], v[82:85]
	s_setprio 0
	s_barrier
	s_add_i32 s75, s61, s41
	s_mov_b32 m0, s75
	ds_read_b128 v[200:203], v181 offset:16384
	ds_read_b128 v[204:207], v181 offset:18432
	ds_read_b128 v[208:211], v182 offset:16384
	ds_read_b128 v[212:215], v182 offset:18432
	ds_read_b128 v[216:219], v181 offset:20480
	ds_read_b128 v[220:223], v181 offset:22528
	ds_read_b128 v[224:227], v182 offset:20480
	ds_read_b128 v[228:231], v182 offset:22528
	global_load_lds_dwordx4 v148, s[56:57]
	s_add_i32 m0, s75, 0x2000
	s_add_u32 s76, s56, 0x4000
	s_addc_u32 s77, s57, 0
	s_add_i32 s75, s62, s41
	global_load_lds_dwordx4 v152, s[56:57]
	s_mov_b32 m0, s75
	v_lshl_add_u64 v[232:233], s[58:59], 0, v[150:151]
	global_load_lds_dwordx4 v148, s[76:77]
	s_add_i32 m0, s75, 0x2000
	s_nop 0
	global_load_lds_dwordx4 v152, s[76:77]
	v_lshl_add_u64 v[168:169], s[58:59], 0, v[146:147]
	s_mov_b32 m0, s42
	s_nop 0
	global_load_lds_dwordx4 v[168:169], off
	s_mov_b32 m0, s43
	s_nop 0
	global_load_lds_dwordx4 v[232:233], off
	s_waitcnt vmcnt(8)
	s_waitcnt lgkmcnt(0)
	s_barrier
	s_setprio 1
	v_mfma_f32_16x16x32_bf16 v[66:69], v[58:61], v[200:203], v[66:69]
	v_mfma_f32_16x16x32_bf16 v[62:65], v[74:77], v[200:203], v[62:65]
	v_mfma_f32_16x16x32_bf16 v[46:49], v[58:61], v[204:207], v[46:49]
	v_mfma_f32_16x16x32_bf16 v[42:45], v[74:77], v[204:207], v[42:45]
	v_mfma_f32_16x16x32_bf16 v[30:33], v[58:61], v[216:219], v[30:33]
	v_mfma_f32_16x16x32_bf16 v[26:29], v[74:77], v[216:219], v[26:29]
	v_mfma_f32_16x16x32_bf16 v[14:17], v[58:61], v[220:223], v[14:17]
	v_mfma_f32_16x16x32_bf16 v[10:13], v[74:77], v[220:223], v[10:13]
	v_mfma_f32_16x16x32_bf16 v[66:69], v[70:73], v[208:211], v[66:69]
	v_mfma_f32_16x16x32_bf16 v[62:65], v[78:81], v[208:211], v[62:65]
	v_mfma_f32_16x16x32_bf16 v[46:49], v[70:73], v[212:215], v[46:49]
	v_mfma_f32_16x16x32_bf16 v[42:45], v[78:81], v[212:215], v[42:45]
	v_mfma_f32_16x16x32_bf16 v[30:33], v[70:73], v[224:227], v[30:33]
	v_mfma_f32_16x16x32_bf16 v[26:29], v[78:81], v[224:227], v[26:29]
	v_mfma_f32_16x16x32_bf16 v[14:17], v[70:73], v[228:231], v[14:17]
	v_mfma_f32_16x16x32_bf16 v[10:13], v[78:81], v[228:231], v[10:13]
	s_setprio 0
	s_setprio 1
	v_mfma_f32_16x16x32_bf16 v[54:57], v[164:167], v[200:203], v[54:57]
	v_mfma_f32_16x16x32_bf16 v[50:53], v[192:195], v[200:203], v[50:53]
	v_mfma_f32_16x16x32_bf16 v[38:41], v[164:167], v[204:207], v[38:41]
	v_mfma_f32_16x16x32_bf16 v[34:37], v[192:195], v[204:207], v[34:37]
	v_mfma_f32_16x16x32_bf16 v[22:25], v[164:167], v[216:219], v[22:25]
	v_mfma_f32_16x16x32_bf16 v[18:21], v[192:195], v[216:219], v[18:21]
	v_mfma_f32_16x16x32_bf16 v[6:9], v[164:167], v[220:223], v[6:9]
	v_mfma_f32_16x16x32_bf16 v[2:5], v[192:195], v[220:223], v[2:5]
	v_mfma_f32_16x16x32_bf16 v[54:57], v[188:191], v[208:211], v[54:57]
	v_mfma_f32_16x16x32_bf16 v[50:53], v[196:199], v[208:211], v[50:53]
	v_mfma_f32_16x16x32_bf16 v[38:41], v[188:191], v[212:215], v[38:41]
	v_mfma_f32_16x16x32_bf16 v[34:37], v[196:199], v[212:215], v[34:37]
	v_mfma_f32_16x16x32_bf16 v[22:25], v[188:191], v[224:227], v[22:25]
	v_mfma_f32_16x16x32_bf16 v[18:21], v[196:199], v[224:227], v[18:21]
	v_mfma_f32_16x16x32_bf16 v[6:9], v[188:191], v[228:231], v[6:9]
	v_mfma_f32_16x16x32_bf16 v[2:5], v[196:199], v[228:231], v[2:5]
	s_setprio 0
	s_barrier
	s_add_i32 s75, 0, 0x18000
	s_add_i32 s76, 0, 0x1c000
	v_add_u32_e32 v58, s75, v171
	v_add_u32_e32 v70, s75, v172
	v_add_u32_e32 v154, s76, v171
	v_add_u32_e32 v188, s76, v172
	ds_read_b128 v[58:61], v58
	ds_read_b128 v[70:73], v70
	ds_read_b128 v[74:77], v183
	ds_read_b128 v[78:81], v184
	ds_read_b128 v[164:167], v154
	ds_read_b128 v[188:191], v188
	ds_read_b128 v[192:195], v185
	ds_read_b128 v[196:199], v186
	s_add_u32 s58, s58, 0x100000
	s_addc_u32 s59, s59, 0
	s_mov_b32 m0, s44
	ds_read_b128 v[200:203], v181 offset:32768
	ds_read_b128 v[204:207], v181 offset:34816
	ds_read_b128 v[208:211], v182 offset:32768
	ds_read_b128 v[212:215], v182 offset:34816
	ds_read_b128 v[216:219], v181 offset:36864
	ds_read_b128 v[220:223], v181 offset:38912
	ds_read_b128 v[224:227], v182 offset:36864
	ds_read_b128 v[228:231], v182 offset:38912
	global_load_lds_dwordx4 v146, s[58:59]
	s_mov_b32 m0, s45
	s_nop 0
	global_load_lds_dwordx4 v150, s[58:59]
	s_waitcnt vmcnt(8)
	s_waitcnt lgkmcnt(0)
	s_barrier
	s_setprio 1
	v_mfma_f32_16x16x32_bf16 v[142:145], v[58:61], v[200:203], v[142:145]
	v_mfma_f32_16x16x32_bf16 v[138:141], v[74:77], v[200:203], v[138:141]
	v_mfma_f32_16x16x32_bf16 v[126:129], v[58:61], v[204:207], v[126:129]
	v_mfma_f32_16x16x32_bf16 v[122:125], v[74:77], v[204:207], v[122:125]
	v_mfma_f32_16x16x32_bf16 v[110:113], v[58:61], v[216:219], v[110:113]
	v_mfma_f32_16x16x32_bf16 v[106:109], v[74:77], v[216:219], v[106:109]
	v_mfma_f32_16x16x32_bf16 v[94:97], v[58:61], v[220:223], v[94:97]
	v_mfma_f32_16x16x32_bf16 v[90:93], v[74:77], v[220:223], v[90:93]
	v_mfma_f32_16x16x32_bf16 v[142:145], v[70:73], v[208:211], v[142:145]
	v_mfma_f32_16x16x32_bf16 v[138:141], v[78:81], v[208:211], v[138:141]
	v_mfma_f32_16x16x32_bf16 v[126:129], v[70:73], v[212:215], v[126:129]
	v_mfma_f32_16x16x32_bf16 v[122:125], v[78:81], v[212:215], v[122:125]
	v_mfma_f32_16x16x32_bf16 v[110:113], v[70:73], v[224:227], v[110:113]
	v_mfma_f32_16x16x32_bf16 v[106:109], v[78:81], v[224:227], v[106:109]
	v_mfma_f32_16x16x32_bf16 v[94:97], v[70:73], v[228:231], v[94:97]
	v_mfma_f32_16x16x32_bf16 v[90:93], v[78:81], v[228:231], v[90:93]
	s_setprio 0
	s_setprio 1
	v_mfma_f32_16x16x32_bf16 v[134:137], v[164:167], v[200:203], v[134:137]
	v_mfma_f32_16x16x32_bf16 v[130:133], v[192:195], v[200:203], v[130:133]
	v_mfma_f32_16x16x32_bf16 v[118:121], v[164:167], v[204:207], v[118:121]
	v_mfma_f32_16x16x32_bf16 v[114:117], v[192:195], v[204:207], v[114:117]
	v_mfma_f32_16x16x32_bf16 v[102:105], v[164:167], v[216:219], v[102:105]
	v_mfma_f32_16x16x32_bf16 v[98:101], v[192:195], v[216:219], v[98:101]
	v_mfma_f32_16x16x32_bf16 v[86:89], v[164:167], v[220:223], v[86:89]
	v_mfma_f32_16x16x32_bf16 v[82:85], v[192:195], v[220:223], v[82:85]
	v_mfma_f32_16x16x32_bf16 v[134:137], v[188:191], v[208:211], v[134:137]
	v_mfma_f32_16x16x32_bf16 v[130:133], v[196:199], v[208:211], v[130:133]
	v_mfma_f32_16x16x32_bf16 v[118:121], v[188:191], v[212:215], v[118:121]
	v_mfma_f32_16x16x32_bf16 v[114:117], v[196:199], v[212:215], v[114:117]
	v_mfma_f32_16x16x32_bf16 v[102:105], v[188:191], v[224:227], v[102:105]
	v_mfma_f32_16x16x32_bf16 v[98:101], v[196:199], v[224:227], v[98:101]
	v_mfma_f32_16x16x32_bf16 v[86:89], v[188:191], v[228:231], v[86:89]
	v_mfma_f32_16x16x32_bf16 v[82:85], v[196:199], v[228:231], v[82:85]
	s_setprio 0
	s_barrier
	s_add_u32 s58, s56, 0x8000
	s_addc_u32 s59, s57, 0
	s_add_i32 s75, s75, s41
	s_mov_b32 m0, s75
	ds_read_b128 v[200:203], v181 offset:49152
	ds_read_b128 v[204:207], v181 offset:51200
	ds_read_b128 v[208:211], v182 offset:49152
	ds_read_b128 v[212:215], v182 offset:51200
	ds_read_b128 v[216:219], v181 offset:53248
	ds_read_b128 v[220:223], v181 offset:55296
	ds_read_b128 v[224:227], v182 offset:53248
	ds_read_b128 v[228:231], v182 offset:55296
	global_load_lds_dwordx4 v148, s[58:59]
	s_add_i32 m0, s75, 0x2000
	s_add_u32 s56, s56, 0xc000
	v_lshl_add_u64 v[234:235], s[58:59], 0, v[152:153]
	s_addc_u32 s57, s57, 0
	s_add_i32 s58, s76, s41
	global_load_lds_dwordx4 v[234:235], off
	s_mov_b32 m0, s58
	v_lshl_add_u64 v[168:169], v[168:169], 0, s[22:23]
	global_load_lds_dwordx4 v148, s[56:57]
	s_add_i32 m0, s58, 0x2000
	s_nop 0
	global_load_lds_dwordx4 v152, s[56:57]
	s_mov_b32 m0, s49
	s_nop 0
	global_load_lds_dwordx4 v[168:169], off
	v_lshl_add_u64 v[168:169], v[232:233], 0, s[22:23]
	s_mov_b32 m0, s50
	s_nop 0
	global_load_lds_dwordx4 v[168:169], off
	s_waitcnt vmcnt(8)
	s_waitcnt lgkmcnt(0)
	s_barrier
	s_setprio 1
	v_mfma_f32_16x16x32_bf16 v[66:69], v[58:61], v[200:203], v[66:69]
	v_mfma_f32_16x16x32_bf16 v[62:65], v[74:77], v[200:203], v[62:65]
	v_mfma_f32_16x16x32_bf16 v[46:49], v[58:61], v[204:207], v[46:49]
	v_mfma_f32_16x16x32_bf16 v[42:45], v[74:77], v[204:207], v[42:45]
	v_mfma_f32_16x16x32_bf16 v[30:33], v[58:61], v[216:219], v[30:33]
	v_mfma_f32_16x16x32_bf16 v[26:29], v[74:77], v[216:219], v[26:29]
	v_mfma_f32_16x16x32_bf16 v[14:17], v[58:61], v[220:223], v[14:17]
	v_mfma_f32_16x16x32_bf16 v[10:13], v[74:77], v[220:223], v[10:13]
	v_mfma_f32_16x16x32_bf16 v[66:69], v[70:73], v[208:211], v[66:69]
	v_mfma_f32_16x16x32_bf16 v[62:65], v[78:81], v[208:211], v[62:65]
	v_mfma_f32_16x16x32_bf16 v[46:49], v[70:73], v[212:215], v[46:49]
	v_mfma_f32_16x16x32_bf16 v[42:45], v[78:81], v[212:215], v[42:45]
	v_mfma_f32_16x16x32_bf16 v[30:33], v[70:73], v[224:227], v[30:33]
	v_mfma_f32_16x16x32_bf16 v[26:29], v[78:81], v[224:227], v[26:29]
	v_mfma_f32_16x16x32_bf16 v[14:17], v[70:73], v[228:231], v[14:17]
	v_mfma_f32_16x16x32_bf16 v[10:13], v[78:81], v[228:231], v[10:13]
	s_setprio 0
	s_setprio 1
	v_mfma_f32_16x16x32_bf16 v[54:57], v[164:167], v[200:203], v[54:57]
	v_mfma_f32_16x16x32_bf16 v[50:53], v[192:195], v[200:203], v[50:53]
	v_mfma_f32_16x16x32_bf16 v[38:41], v[164:167], v[204:207], v[38:41]
	v_mfma_f32_16x16x32_bf16 v[34:37], v[192:195], v[204:207], v[34:37]
	v_mfma_f32_16x16x32_bf16 v[22:25], v[164:167], v[216:219], v[22:25]
	v_mfma_f32_16x16x32_bf16 v[18:21], v[192:195], v[216:219], v[18:21]
	v_mfma_f32_16x16x32_bf16 v[6:9], v[164:167], v[220:223], v[6:9]
	v_mfma_f32_16x16x32_bf16 v[2:5], v[192:195], v[220:223], v[2:5]
	v_mfma_f32_16x16x32_bf16 v[54:57], v[188:191], v[208:211], v[54:57]
	v_mfma_f32_16x16x32_bf16 v[50:53], v[196:199], v[208:211], v[50:53]
	v_mfma_f32_16x16x32_bf16 v[38:41], v[188:191], v[212:215], v[38:41]
	v_mfma_f32_16x16x32_bf16 v[34:37], v[196:199], v[212:215], v[34:37]
	v_mfma_f32_16x16x32_bf16 v[22:25], v[188:191], v[224:227], v[22:25]
	v_mfma_f32_16x16x32_bf16 v[18:21], v[196:199], v[224:227], v[18:21]
	v_mfma_f32_16x16x32_bf16 v[6:9], v[188:191], v[228:231], v[6:9]
	v_mfma_f32_16x16x32_bf16 v[2:5], v[196:199], v[228:231], v[2:5]
	s_setprio 0
	s_barrier
	s_add_i32 s74, s74, 2
	s_add_u32 s72, s72, 0x10000
	s_addc_u32 s73, s73, 0
	s_add_u32 s54, s54, 0x100
	s_addc_u32 s55, s55, 0
	s_cmp_gt_u32 s74, 61
	s_cbranch_scc0 .LBB0_495
	s_and_b64 vcc, exec, s[24:25]
	s_cbranch_vccz .LBB0_498
	s_barrier

.LBB0_690:
	ds_read_b128 v[148:151], v155
	ds_read_b128 v[170:173], v156
	ds_read_b128 v[174:177], v157
	ds_read_b128 v[178:181], v158
	ds_read_b128 v[182:185], v159
	ds_read_b128 v[186:189], v160
	ds_read_b128 v[190:193], v161
	ds_read_b128 v[194:197], v162
	s_add_u32 s26, s24, 0x4000
	s_addc_u32 s27, s25, 0
	s_cmp_eq_u32 s59, 60
	s_cselect_b32 s30, s55, s26
	s_cselect_b32 s31, s17, s27
	s_cselect_b32 s28, s56, s57
	s_cselect_b32 s29, s15, s58
	s_add_u32 s26, s30, 0x8000
	s_addc_u32 s27, s31, 0
	s_add_i32 m0, s39, 0xc000
	ds_read_b128 v[198:201], v163
	ds_read_b128 v[202:205], v163 offset:2048
	ds_read_b128 v[206:209], v164
	ds_read_b128 v[210:213], v164 offset:2048
	ds_read_b128 v[214:217], v163 offset:4096
	ds_read_b128 v[218:221], v163 offset:6144
	ds_read_b128 v[222:225], v164 offset:4096
	ds_read_b128 v[226:229], v164 offset:6144
	global_load_lds_dwordx4 v140, s[24:25]
	s_add_i32 m0, s39, 0xe000
	s_nop 0
	global_load_lds_dwordx4 v142, s[24:25]
	s_waitcnt vmcnt(8)
	s_waitcnt lgkmcnt(0)
	s_barrier
	s_setprio 1
	v_mfma_f32_16x16x32_bf16 v[126:129], v[148:151], v[198:201], v[126:129]
	v_mfma_f32_16x16x32_bf16 v[122:125], v[174:177], v[198:201], v[122:125]
	v_mfma_f32_16x16x32_bf16 v[110:113], v[148:151], v[202:205], v[110:113]
	v_mfma_f32_16x16x32_bf16 v[106:109], v[174:177], v[202:205], v[106:109]
	v_mfma_f32_16x16x32_bf16 v[94:97], v[148:151], v[214:217], v[94:97]
	v_mfma_f32_16x16x32_bf16 v[90:93], v[174:177], v[214:217], v[90:93]
	v_mfma_f32_16x16x32_bf16 v[78:81], v[148:151], v[218:221], v[78:81]
	v_mfma_f32_16x16x32_bf16 v[74:77], v[174:177], v[218:221], v[74:77]
	v_mfma_f32_16x16x32_bf16 v[126:129], v[170:173], v[206:209], v[126:129]
	v_mfma_f32_16x16x32_bf16 v[122:125], v[178:181], v[206:209], v[122:125]
	v_mfma_f32_16x16x32_bf16 v[110:113], v[170:173], v[210:213], v[110:113]
	v_mfma_f32_16x16x32_bf16 v[106:109], v[178:181], v[210:213], v[106:109]
	v_mfma_f32_16x16x32_bf16 v[94:97], v[170:173], v[222:225], v[94:97]
	v_mfma_f32_16x16x32_bf16 v[90:93], v[178:181], v[222:225], v[90:93]
	v_mfma_f32_16x16x32_bf16 v[78:81], v[170:173], v[226:229], v[78:81]
	v_mfma_f32_16x16x32_bf16 v[74:77], v[178:181], v[226:229], v[74:77]
	s_setprio 0
	s_setprio 1
	v_mfma_f32_16x16x32_bf16 v[118:121], v[182:185], v[198:201], v[118:121]
	v_mfma_f32_16x16x32_bf16 v[114:117], v[190:193], v[198:201], v[114:117]
	v_mfma_f32_16x16x32_bf16 v[102:105], v[182:185], v[202:205], v[102:105]
	v_mfma_f32_16x16x32_bf16 v[98:101], v[190:193], v[202:205], v[98:101]
	v_mfma_f32_16x16x32_bf16 v[86:89], v[182:185], v[214:217], v[86:89]
	v_mfma_f32_16x16x32_bf16 v[82:85], v[190:193], v[214:217], v[82:85]
	v_mfma_f32_16x16x32_bf16 v[70:73], v[182:185], v[218:221], v[70:73]
	v_mfma_f32_16x16x32_bf16 v[66:69], v[190:193], v[218:221], v[66:69]
	v_mfma_f32_16x16x32_bf16 v[118:121], v[186:189], v[206:209], v[118:121]
	v_mfma_f32_16x16x32_bf16 v[114:117], v[194:197], v[206:209], v[114:117]
	v_mfma_f32_16x16x32_bf16 v[102:105], v[186:189], v[210:213], v[102:105]
	v_mfma_f32_16x16x32_bf16 v[98:101], v[194:197], v[210:213], v[98:101]
	v_mfma_f32_16x16x32_bf16 v[86:89], v[186:189], v[222:225], v[86:89]
	v_mfma_f32_16x16x32_bf16 v[82:85], v[194:197], v[222:225], v[82:85]
	v_mfma_f32_16x16x32_bf16 v[70:73], v[186:189], v[226:229], v[70:73]
	v_mfma_f32_16x16x32_bf16 v[66:69], v[194:197], v[226:229], v[66:69]
	s_setprio 0
	s_barrier
	s_add_i32 s60, s49, s38
	s_mov_b32 m0, s60
	ds_read_b128 v[198:201], v163 offset:16384
	ds_read_b128 v[202:205], v163 offset:18432
	ds_read_b128 v[206:209], v164 offset:16384
	ds_read_b128 v[210:213], v164 offset:18432
	ds_read_b128 v[214:217], v163 offset:20480
	ds_read_b128 v[218:221], v163 offset:22528
	ds_read_b128 v[222:225], v164 offset:20480
	ds_read_b128 v[226:229], v164 offset:22528
	global_load_lds_dwordx4 v132, s[28:29]
	s_add_i32 m0, s60, 0x2000
	s_add_u32 s60, s28, 0x4000
	s_addc_u32 s61, s29, 0
	s_add_i32 s62, s50, s38
	global_load_lds_dwordx4 v136, s[28:29]
	s_mov_b32 m0, s62
	s_nop 0
	global_load_lds_dwordx4 v132, s[60:61]
	s_add_i32 m0, s62, 0x2000
	s_nop 0
	global_load_lds_dwordx4 v136, s[60:61]
	s_mov_b32 m0, s39
	s_nop 0
	global_load_lds_dwordx4 v130, s[30:31]
	s_mov_b32 m0, s40
	s_nop 0
	global_load_lds_dwordx4 v134, s[30:31]
	s_waitcnt vmcnt(8)
	s_waitcnt lgkmcnt(0)
	s_barrier
	s_setprio 1
	v_mfma_f32_16x16x32_bf16 v[62:65], v[148:151], v[198:201], v[62:65]
	v_mfma_f32_16x16x32_bf16 v[58:61], v[174:177], v[198:201], v[58:61]
	v_mfma_f32_16x16x32_bf16 v[46:49], v[148:151], v[202:205], v[46:49]
	v_mfma_f32_16x16x32_bf16 v[42:45], v[174:177], v[202:205], v[42:45]
	v_mfma_f32_16x16x32_bf16 v[30:33], v[148:151], v[214:217], v[30:33]
	v_mfma_f32_16x16x32_bf16 v[26:29], v[174:177], v[214:217], v[26:29]
	v_mfma_f32_16x16x32_bf16 v[14:17], v[148:151], v[218:221], v[14:17]
	v_mfma_f32_16x16x32_bf16 v[10:13], v[174:177], v[218:221], v[10:13]
	v_mfma_f32_16x16x32_bf16 v[62:65], v[170:173], v[206:209], v[62:65]
	v_mfma_f32_16x16x32_bf16 v[58:61], v[178:181], v[206:209], v[58:61]
	v_mfma_f32_16x16x32_bf16 v[46:49], v[170:173], v[210:213], v[46:49]
	v_mfma_f32_16x16x32_bf16 v[42:45], v[178:181], v[210:213], v[42:45]
	v_mfma_f32_16x16x32_bf16 v[30:33], v[170:173], v[222:225], v[30:33]
	v_mfma_f32_16x16x32_bf16 v[26:29], v[178:181], v[222:225], v[26:29]
	v_mfma_f32_16x16x32_bf16 v[14:17], v[170:173], v[226:229], v[14:17]
	v_mfma_f32_16x16x32_bf16 v[10:13], v[178:181], v[226:229], v[10:13]
	s_setprio 0
	s_setprio 1
	v_mfma_f32_16x16x32_bf16 v[54:57], v[182:185], v[198:201], v[54:57]
	v_mfma_f32_16x16x32_bf16 v[50:53], v[190:193], v[198:201], v[50:53]
	v_mfma_f32_16x16x32_bf16 v[38:41], v[182:185], v[202:205], v[38:41]
	v_mfma_f32_16x16x32_bf16 v[34:37], v[190:193], v[202:205], v[34:37]
	v_mfma_f32_16x16x32_bf16 v[22:25], v[182:185], v[214:217], v[22:25]
	v_mfma_f32_16x16x32_bf16 v[18:21], v[190:193], v[214:217], v[18:21]
	v_mfma_f32_16x16x32_bf16 v[6:9], v[182:185], v[218:221], v[6:9]
	v_mfma_f32_16x16x32_bf16 v[2:5], v[190:193], v[218:221], v[2:5]
	v_mfma_f32_16x16x32_bf16 v[54:57], v[186:189], v[206:209], v[54:57]
	v_mfma_f32_16x16x32_bf16 v[50:53], v[194:197], v[206:209], v[50:53]
	v_mfma_f32_16x16x32_bf16 v[38:41], v[186:189], v[210:213], v[38:41]
	v_mfma_f32_16x16x32_bf16 v[34:37], v[194:197], v[210:213], v[34:37]
	v_mfma_f32_16x16x32_bf16 v[22:25], v[186:189], v[222:225], v[22:25]
	v_mfma_f32_16x16x32_bf16 v[18:21], v[194:197], v[222:225], v[18:21]
	v_mfma_f32_16x16x32_bf16 v[6:9], v[186:189], v[226:229], v[6:9]
	v_mfma_f32_16x16x32_bf16 v[2:5], v[194:197], v[226:229], v[2:5]
	s_setprio 0
	s_barrier
	s_add_i32 s60, 0, 0x18000
	v_add_u32_e32 v138, s60, v152
	v_add_u32_e32 v170, s60, v153
	s_add_i32 s61, 0, 0x1c000
	ds_read_b128 v[148:151], v138
	ds_read_b128 v[170:173], v170
	ds_read_b128 v[174:177], v165
	ds_read_b128 v[178:181], v166
	v_add_u32_e32 v138, s61, v152
	v_add_u32_e32 v186, s61, v153
	ds_read_b128 v[182:185], v138
	ds_read_b128 v[186:189], v186
	ds_read_b128 v[190:193], v167
	ds_read_b128 v[194:197], v168
	s_add_u32 s30, s30, 0x4000
	s_addc_u32 s31, s31, 0
	s_mov_b32 m0, s41
	ds_read_b128 v[198:201], v163 offset:32768
	ds_read_b128 v[202:205], v163 offset:34816
	ds_read_b128 v[206:209], v164 offset:32768
	ds_read_b128 v[210:213], v164 offset:34816
	ds_read_b128 v[214:217], v163 offset:36864
	ds_read_b128 v[218:221], v163 offset:38912
	ds_read_b128 v[222:225], v164 offset:36864
	ds_read_b128 v[226:229], v164 offset:38912
	global_load_lds_dwordx4 v130, s[30:31]
	s_mov_b32 m0, s42
	s_nop 0
	global_load_lds_dwordx4 v134, s[30:31]
	s_waitcnt vmcnt(8)
	s_waitcnt lgkmcnt(0)
	s_barrier
	s_setprio 1
	v_mfma_f32_16x16x32_bf16 v[126:129], v[148:151], v[198:201], v[126:129]
	v_mfma_f32_16x16x32_bf16 v[122:125], v[174:177], v[198:201], v[122:125]
	v_mfma_f32_16x16x32_bf16 v[110:113], v[148:151], v[202:205], v[110:113]
	v_mfma_f32_16x16x32_bf16 v[106:109], v[174:177], v[202:205], v[106:109]
	v_mfma_f32_16x16x32_bf16 v[94:97], v[148:151], v[214:217], v[94:97]
	v_mfma_f32_16x16x32_bf16 v[90:93], v[174:177], v[214:217], v[90:93]
	v_mfma_f32_16x16x32_bf16 v[78:81], v[148:151], v[218:221], v[78:81]
	v_mfma_f32_16x16x32_bf16 v[74:77], v[174:177], v[218:221], v[74:77]
	v_mfma_f32_16x16x32_bf16 v[126:129], v[170:173], v[206:209], v[126:129]
	v_mfma_f32_16x16x32_bf16 v[122:125], v[178:181], v[206:209], v[122:125]
	v_mfma_f32_16x16x32_bf16 v[110:113], v[170:173], v[210:213], v[110:113]
	v_mfma_f32_16x16x32_bf16 v[106:109], v[178:181], v[210:213], v[106:109]
	v_mfma_f32_16x16x32_bf16 v[94:97], v[170:173], v[222:225], v[94:97]
	v_mfma_f32_16x16x32_bf16 v[90:93], v[178:181], v[222:225], v[90:93]
	v_mfma_f32_16x16x32_bf16 v[78:81], v[170:173], v[226:229], v[78:81]
	v_mfma_f32_16x16x32_bf16 v[74:77], v[178:181], v[226:229], v[74:77]
	s_setprio 0
	s_setprio 1
	v_mfma_f32_16x16x32_bf16 v[118:121], v[182:185], v[198:201], v[118:121]
	v_mfma_f32_16x16x32_bf16 v[114:117], v[190:193], v[198:201], v[114:117]
	v_mfma_f32_16x16x32_bf16 v[102:105], v[182:185], v[202:205], v[102:105]
	v_mfma_f32_16x16x32_bf16 v[98:101], v[190:193], v[202:205], v[98:101]
	v_mfma_f32_16x16x32_bf16 v[86:89], v[182:185], v[214:217], v[86:89]
	v_mfma_f32_16x16x32_bf16 v[82:85], v[190:193], v[214:217], v[82:85]
	v_mfma_f32_16x16x32_bf16 v[70:73], v[182:185], v[218:221], v[70:73]
	v_mfma_f32_16x16x32_bf16 v[66:69], v[190:193], v[218:221], v[66:69]
	v_mfma_f32_16x16x32_bf16 v[118:121], v[186:189], v[206:209], v[118:121]
	v_mfma_f32_16x16x32_bf16 v[114:117], v[194:197], v[206:209], v[114:117]
	v_mfma_f32_16x16x32_bf16 v[102:105], v[186:189], v[210:213], v[102:105]
	v_mfma_f32_16x16x32_bf16 v[98:101], v[194:197], v[210:213], v[98:101]
	v_mfma_f32_16x16x32_bf16 v[86:89], v[186:189], v[222:225], v[86:89]
	v_mfma_f32_16x16x32_bf16 v[82:85], v[194:197], v[222:225], v[82:85]
	v_mfma_f32_16x16x32_bf16 v[70:73], v[186:189], v[226:229], v[70:73]
	v_mfma_f32_16x16x32_bf16 v[66:69], v[194:197], v[226:229], v[66:69]
	s_setprio 0
	s_barrier
	s_add_u32 s30, s28, 0x8000
	s_addc_u32 s31, s29, 0
	s_add_i32 s60, s60, s38
	s_mov_b32 m0, s60
	ds_read_b128 v[198:201], v163 offset:49152
	ds_read_b128 v[202:205], v163 offset:51200
	ds_read_b128 v[206:209], v164 offset:49152
	ds_read_b128 v[210:213], v164 offset:51200
	ds_read_b128 v[214:217], v163 offset:53248
	ds_read_b128 v[218:221], v163 offset:55296
	ds_read_b128 v[222:225], v164 offset:53248
	ds_read_b128 v[226:229], v164 offset:55296
	global_load_lds_dwordx4 v132, s[30:31]
	s_add_i32 m0, s60, 0x2000
	s_add_u32 s28, s28, 0xc000
	v_lshl_add_u64 v[230:231], s[30:31], 0, v[136:137]
	s_addc_u32 s29, s29, 0
	s_add_i32 s30, s61, s38
	global_load_lds_dwordx4 v[230:231], off
	s_mov_b32 m0, s30
	s_nop 0
	global_load_lds_dwordx4 v132, s[28:29]
	s_add_i32 m0, s30, 0x2000
	s_nop 0
	global_load_lds_dwordx4 v136, s[28:29]
	s_mov_b32 m0, s46
	s_nop 0
	global_load_lds_dwordx4 v130, s[26:27]
	s_mov_b32 m0, s47
	s_nop 0
	global_load_lds_dwordx4 v134, s[26:27]
	s_waitcnt vmcnt(8)
	s_waitcnt lgkmcnt(0)
	s_barrier
	s_setprio 1
	v_mfma_f32_16x16x32_bf16 v[62:65], v[148:151], v[198:201], v[62:65]
	v_mfma_f32_16x16x32_bf16 v[58:61], v[174:177], v[198:201], v[58:61]
	v_mfma_f32_16x16x32_bf16 v[46:49], v[148:151], v[202:205], v[46:49]
	v_mfma_f32_16x16x32_bf16 v[42:45], v[174:177], v[202:205], v[42:45]
	v_mfma_f32_16x16x32_bf16 v[30:33], v[148:151], v[214:217], v[30:33]
	v_mfma_f32_16x16x32_bf16 v[26:29], v[174:177], v[214:217], v[26:29]
	v_mfma_f32_16x16x32_bf16 v[14:17], v[148:151], v[218:221], v[14:17]
	v_mfma_f32_16x16x32_bf16 v[10:13], v[174:177], v[218:221], v[10:13]
	v_mfma_f32_16x16x32_bf16 v[62:65], v[170:173], v[206:209], v[62:65]
	v_mfma_f32_16x16x32_bf16 v[58:61], v[178:181], v[206:209], v[58:61]
	v_mfma_f32_16x16x32_bf16 v[46:49], v[170:173], v[210:213], v[46:49]
	v_mfma_f32_16x16x32_bf16 v[42:45], v[178:181], v[210:213], v[42:45]
	v_mfma_f32_16x16x32_bf16 v[30:33], v[170:173], v[222:225], v[30:33]
	v_mfma_f32_16x16x32_bf16 v[26:29], v[178:181], v[222:225], v[26:29]
	v_mfma_f32_16x16x32_bf16 v[14:17], v[170:173], v[226:229], v[14:17]
	v_mfma_f32_16x16x32_bf16 v[10:13], v[178:181], v[226:229], v[10:13]
	s_setprio 0
	s_setprio 1
	v_mfma_f32_16x16x32_bf16 v[54:57], v[182:185], v[198:201], v[54:57]
	v_mfma_f32_16x16x32_bf16 v[50:53], v[190:193], v[198:201], v[50:53]
	v_mfma_f32_16x16x32_bf16 v[38:41], v[182:185], v[202:205], v[38:41]
	v_mfma_f32_16x16x32_bf16 v[34:37], v[190:193], v[202:205], v[34:37]
	v_mfma_f32_16x16x32_bf16 v[22:25], v[182:185], v[214:217], v[22:25]
	v_mfma_f32_16x16x32_bf16 v[18:21], v[190:193], v[214:217], v[18:21]
	v_mfma_f32_16x16x32_bf16 v[6:9], v[182:185], v[218:221], v[6:9]
	v_mfma_f32_16x16x32_bf16 v[2:5], v[190:193], v[218:221], v[2:5]
	v_mfma_f32_16x16x32_bf16 v[54:57], v[186:189], v[206:209], v[54:57]
	v_mfma_f32_16x16x32_bf16 v[50:53], v[194:197], v[206:209], v[50:53]
	v_mfma_f32_16x16x32_bf16 v[38:41], v[186:189], v[210:213], v[38:41]
	v_mfma_f32_16x16x32_bf16 v[34:37], v[194:197], v[210:213], v[34:37]
	v_mfma_f32_16x16x32_bf16 v[22:25], v[186:189], v[222:225], v[22:25]
	v_mfma_f32_16x16x32_bf16 v[18:21], v[194:197], v[222:225], v[18:21]
	v_mfma_f32_16x16x32_bf16 v[6:9], v[186:189], v[226:229], v[6:9]
	v_mfma_f32_16x16x32_bf16 v[2:5], v[194:197], v[226:229], v[2:5]
	s_setprio 0
	s_barrier
	s_add_i32 s59, s59, 2
	s_add_u32 s24, s24, 0x10000
	s_addc_u32 s25, s25, 0
	s_add_u32 s57, s57, 0x10000
	s_addc_u32 s58, s58, 0
	s_cmp_gt_u32 s59, 61
	s_cbranch_scc0 .LBB0_690
	s_and_b64 vcc, exec, s[12:13]
	s_cbranch_vccz .LBB0_693
	s_barrier

.LBB0_778:
	ds_read_b128 v[146:149], v153
	ds_read_b128 v[168:171], v154
	ds_read_b128 v[172:175], v155
	ds_read_b128 v[176:179], v156
	ds_read_b128 v[180:183], v157
	ds_read_b128 v[184:187], v158
	ds_read_b128 v[188:191], v159
	ds_read_b128 v[192:195], v160
	s_add_u32 s36, s30, 0x4000
	s_addc_u32 s37, s31, 0
	s_cmpk_eq_i32 s57, 0xfc
	s_cselect_b32 s52, s27, s36
	s_cselect_b32 s53, s21, s37
	s_cselect_b32 s38, s54, s55
	s_cselect_b32 s39, s19, s56
	s_add_u32 s36, s52, 0x8000
	s_addc_u32 s37, s53, 0
	s_add_i32 m0, s29, 0xc000
	ds_read_b128 v[196:199], v161
	ds_read_b128 v[200:203], v161 offset:2048
	ds_read_b128 v[204:207], v162
	ds_read_b128 v[208:211], v162 offset:2048
	ds_read_b128 v[212:215], v161 offset:4096
	ds_read_b128 v[216:219], v161 offset:6144
	ds_read_b128 v[220:223], v162 offset:4096
	ds_read_b128 v[224:227], v162 offset:6144
	global_load_lds_dwordx4 v138, s[30:31]
	s_add_i32 m0, s29, 0xe000
	s_nop 0
	global_load_lds_dwordx4 v140, s[30:31]
	s_waitcnt vmcnt(8)
	s_waitcnt lgkmcnt(0)
	s_barrier
	s_setprio 1
	v_mfma_f32_16x16x32_bf16 v[126:129], v[146:149], v[196:199], v[126:129]
	v_mfma_f32_16x16x32_bf16 v[122:125], v[172:175], v[196:199], v[122:125]
	v_mfma_f32_16x16x32_bf16 v[110:113], v[146:149], v[200:203], v[110:113]
	v_mfma_f32_16x16x32_bf16 v[106:109], v[172:175], v[200:203], v[106:109]
	v_mfma_f32_16x16x32_bf16 v[94:97], v[146:149], v[212:215], v[94:97]
	v_mfma_f32_16x16x32_bf16 v[90:93], v[172:175], v[212:215], v[90:93]
	v_mfma_f32_16x16x32_bf16 v[78:81], v[146:149], v[216:219], v[78:81]
	v_mfma_f32_16x16x32_bf16 v[74:77], v[172:175], v[216:219], v[74:77]
	v_mfma_f32_16x16x32_bf16 v[126:129], v[168:171], v[204:207], v[126:129]
	v_mfma_f32_16x16x32_bf16 v[122:125], v[176:179], v[204:207], v[122:125]
	v_mfma_f32_16x16x32_bf16 v[110:113], v[168:171], v[208:211], v[110:113]
	v_mfma_f32_16x16x32_bf16 v[106:109], v[176:179], v[208:211], v[106:109]
	v_mfma_f32_16x16x32_bf16 v[94:97], v[168:171], v[220:223], v[94:97]
	v_mfma_f32_16x16x32_bf16 v[90:93], v[176:179], v[220:223], v[90:93]
	v_mfma_f32_16x16x32_bf16 v[78:81], v[168:171], v[224:227], v[78:81]
	v_mfma_f32_16x16x32_bf16 v[74:77], v[176:179], v[224:227], v[74:77]
	s_setprio 0
	s_setprio 1
	v_mfma_f32_16x16x32_bf16 v[118:121], v[180:183], v[196:199], v[118:121]
	v_mfma_f32_16x16x32_bf16 v[114:117], v[188:191], v[196:199], v[114:117]
	v_mfma_f32_16x16x32_bf16 v[102:105], v[180:183], v[200:203], v[102:105]
	v_mfma_f32_16x16x32_bf16 v[98:101], v[188:191], v[200:203], v[98:101]
	v_mfma_f32_16x16x32_bf16 v[86:89], v[180:183], v[212:215], v[86:89]
	v_mfma_f32_16x16x32_bf16 v[82:85], v[188:191], v[212:215], v[82:85]
	v_mfma_f32_16x16x32_bf16 v[70:73], v[180:183], v[216:219], v[70:73]
	v_mfma_f32_16x16x32_bf16 v[66:69], v[188:191], v[216:219], v[66:69]
	v_mfma_f32_16x16x32_bf16 v[118:121], v[184:187], v[204:207], v[118:121]
	v_mfma_f32_16x16x32_bf16 v[114:117], v[192:195], v[204:207], v[114:117]
	v_mfma_f32_16x16x32_bf16 v[102:105], v[184:187], v[208:211], v[102:105]
	v_mfma_f32_16x16x32_bf16 v[98:101], v[192:195], v[208:211], v[98:101]
	v_mfma_f32_16x16x32_bf16 v[86:89], v[184:187], v[220:223], v[86:89]
	v_mfma_f32_16x16x32_bf16 v[82:85], v[192:195], v[220:223], v[82:85]
	v_mfma_f32_16x16x32_bf16 v[70:73], v[184:187], v[224:227], v[70:73]
	v_mfma_f32_16x16x32_bf16 v[66:69], v[192:195], v[224:227], v[66:69]
	s_setprio 0
	s_barrier
	s_add_i32 s58, s50, s41
	s_mov_b32 m0, s58
	ds_read_b128 v[196:199], v161 offset:16384
	ds_read_b128 v[200:203], v161 offset:18432
	ds_read_b128 v[204:207], v162 offset:16384
	ds_read_b128 v[208:211], v162 offset:18432
	ds_read_b128 v[212:215], v161 offset:20480
	ds_read_b128 v[216:219], v161 offset:22528
	ds_read_b128 v[220:223], v162 offset:20480
	ds_read_b128 v[224:227], v162 offset:22528
	global_load_lds_dwordx4 v132, s[38:39]
	s_add_i32 m0, s58, 0x2000
	s_add_u32 s58, s38, 0x4000
	s_addc_u32 s59, s39, 0
	s_add_i32 s60, s51, s41
	global_load_lds_dwordx4 v136, s[38:39]
	s_mov_b32 m0, s60
	s_nop 0
	global_load_lds_dwordx4 v132, s[58:59]
	s_add_i32 m0, s60, 0x2000
	s_nop 0
	global_load_lds_dwordx4 v136, s[58:59]
	s_mov_b32 m0, s29
	s_nop 0
	global_load_lds_dwordx4 v130, s[52:53]
	s_mov_b32 m0, s42
	s_nop 0
	global_load_lds_dwordx4 v134, s[52:53]
	s_waitcnt vmcnt(8)
	s_waitcnt lgkmcnt(0)
	s_barrier
	s_setprio 1
	v_mfma_f32_16x16x32_bf16 v[62:65], v[146:149], v[196:199], v[62:65]
	v_mfma_f32_16x16x32_bf16 v[58:61], v[172:175], v[196:199], v[58:61]
	v_mfma_f32_16x16x32_bf16 v[46:49], v[146:149], v[200:203], v[46:49]
	v_mfma_f32_16x16x32_bf16 v[42:45], v[172:175], v[200:203], v[42:45]
	v_mfma_f32_16x16x32_bf16 v[30:33], v[146:149], v[212:215], v[30:33]
	v_mfma_f32_16x16x32_bf16 v[26:29], v[172:175], v[212:215], v[26:29]
	v_mfma_f32_16x16x32_bf16 v[14:17], v[146:149], v[216:219], v[14:17]
	v_mfma_f32_16x16x32_bf16 v[10:13], v[172:175], v[216:219], v[10:13]
	v_mfma_f32_16x16x32_bf16 v[62:65], v[168:171], v[204:207], v[62:65]
	v_mfma_f32_16x16x32_bf16 v[58:61], v[176:179], v[204:207], v[58:61]
	v_mfma_f32_16x16x32_bf16 v[46:49], v[168:171], v[208:211], v[46:49]
	v_mfma_f32_16x16x32_bf16 v[42:45], v[176:179], v[208:211], v[42:45]
	v_mfma_f32_16x16x32_bf16 v[30:33], v[168:171], v[220:223], v[30:33]
	v_mfma_f32_16x16x32_bf16 v[26:29], v[176:179], v[220:223], v[26:29]
	v_mfma_f32_16x16x32_bf16 v[14:17], v[168:171], v[224:227], v[14:17]
	v_mfma_f32_16x16x32_bf16 v[10:13], v[176:179], v[224:227], v[10:13]
	s_setprio 0
	s_setprio 1
	v_mfma_f32_16x16x32_bf16 v[54:57], v[180:183], v[196:199], v[54:57]
	v_mfma_f32_16x16x32_bf16 v[50:53], v[188:191], v[196:199], v[50:53]
	v_mfma_f32_16x16x32_bf16 v[38:41], v[180:183], v[200:203], v[38:41]
	v_mfma_f32_16x16x32_bf16 v[34:37], v[188:191], v[200:203], v[34:37]
	v_mfma_f32_16x16x32_bf16 v[22:25], v[180:183], v[212:215], v[22:25]
	v_mfma_f32_16x16x32_bf16 v[18:21], v[188:191], v[212:215], v[18:21]
	v_mfma_f32_16x16x32_bf16 v[6:9], v[180:183], v[216:219], v[6:9]
	v_mfma_f32_16x16x32_bf16 v[2:5], v[188:191], v[216:219], v[2:5]
	v_mfma_f32_16x16x32_bf16 v[54:57], v[184:187], v[204:207], v[54:57]
	v_mfma_f32_16x16x32_bf16 v[50:53], v[192:195], v[204:207], v[50:53]
	v_mfma_f32_16x16x32_bf16 v[38:41], v[184:187], v[208:211], v[38:41]
	v_mfma_f32_16x16x32_bf16 v[34:37], v[192:195], v[208:211], v[34:37]
	v_mfma_f32_16x16x32_bf16 v[22:25], v[184:187], v[220:223], v[22:25]
	v_mfma_f32_16x16x32_bf16 v[18:21], v[192:195], v[220:223], v[18:21]
	v_mfma_f32_16x16x32_bf16 v[6:9], v[184:187], v[224:227], v[6:9]
	v_mfma_f32_16x16x32_bf16 v[2:5], v[192:195], v[224:227], v[2:5]
	s_setprio 0
	s_barrier
	s_add_i32 s58, 0, 0x18000
	s_add_i32 s59, 0, 0x1c000
	v_add_u32_e32 v146, s58, v150
	v_add_u32_e32 v168, s58, v151
	v_add_u32_e32 v180, s59, v150
	v_add_u32_e32 v184, s59, v151
	ds_read_b128 v[146:149], v146
	ds_read_b128 v[168:171], v168
	ds_read_b128 v[172:175], v163
	ds_read_b128 v[176:179], v164
	ds_read_b128 v[180:183], v180
	ds_read_b128 v[184:187], v184
	ds_read_b128 v[188:191], v165
	ds_read_b128 v[192:195], v166
	s_add_u32 s52, s52, 0x4000
	s_addc_u32 s53, s53, 0
	s_mov_b32 m0, s43
	ds_read_b128 v[196:199], v161 offset:32768
	ds_read_b128 v[200:203], v161 offset:34816
	ds_read_b128 v[204:207], v162 offset:32768
	ds_read_b128 v[208:211], v162 offset:34816
	ds_read_b128 v[212:215], v161 offset:36864
	ds_read_b128 v[216:219], v161 offset:38912
	ds_read_b128 v[220:223], v162 offset:36864
	ds_read_b128 v[224:227], v162 offset:38912
	global_load_lds_dwordx4 v130, s[52:53]
	s_mov_b32 m0, s44
	s_nop 0
	global_load_lds_dwordx4 v134, s[52:53]
	s_waitcnt vmcnt(8)
	s_waitcnt lgkmcnt(0)
	s_barrier
	s_setprio 1
	v_mfma_f32_16x16x32_bf16 v[126:129], v[146:149], v[196:199], v[126:129]
	v_mfma_f32_16x16x32_bf16 v[122:125], v[172:175], v[196:199], v[122:125]
	v_mfma_f32_16x16x32_bf16 v[110:113], v[146:149], v[200:203], v[110:113]
	v_mfma_f32_16x16x32_bf16 v[106:109], v[172:175], v[200:203], v[106:109]
	v_mfma_f32_16x16x32_bf16 v[94:97], v[146:149], v[212:215], v[94:97]
	v_mfma_f32_16x16x32_bf16 v[90:93], v[172:175], v[212:215], v[90:93]
	v_mfma_f32_16x16x32_bf16 v[78:81], v[146:149], v[216:219], v[78:81]
	v_mfma_f32_16x16x32_bf16 v[74:77], v[172:175], v[216:219], v[74:77]
	v_mfma_f32_16x16x32_bf16 v[126:129], v[168:171], v[204:207], v[126:129]
	v_mfma_f32_16x16x32_bf16 v[122:125], v[176:179], v[204:207], v[122:125]
	v_mfma_f32_16x16x32_bf16 v[110:113], v[168:171], v[208:211], v[110:113]
	v_mfma_f32_16x16x32_bf16 v[106:109], v[176:179], v[208:211], v[106:109]
	v_mfma_f32_16x16x32_bf16 v[94:97], v[168:171], v[220:223], v[94:97]
	v_mfma_f32_16x16x32_bf16 v[90:93], v[176:179], v[220:223], v[90:93]
	v_mfma_f32_16x16x32_bf16 v[78:81], v[168:171], v[224:227], v[78:81]
	v_mfma_f32_16x16x32_bf16 v[74:77], v[176:179], v[224:227], v[74:77]
	s_setprio 0
	s_setprio 1
	v_mfma_f32_16x16x32_bf16 v[118:121], v[180:183], v[196:199], v[118:121]
	v_mfma_f32_16x16x32_bf16 v[114:117], v[188:191], v[196:199], v[114:117]
	v_mfma_f32_16x16x32_bf16 v[102:105], v[180:183], v[200:203], v[102:105]
	v_mfma_f32_16x16x32_bf16 v[98:101], v[188:191], v[200:203], v[98:101]
	v_mfma_f32_16x16x32_bf16 v[86:89], v[180:183], v[212:215], v[86:89]
	v_mfma_f32_16x16x32_bf16 v[82:85], v[188:191], v[212:215], v[82:85]
	v_mfma_f32_16x16x32_bf16 v[70:73], v[180:183], v[216:219], v[70:73]
	v_mfma_f32_16x16x32_bf16 v[66:69], v[188:191], v[216:219], v[66:69]
	v_mfma_f32_16x16x32_bf16 v[118:121], v[184:187], v[204:207], v[118:121]
	v_mfma_f32_16x16x32_bf16 v[114:117], v[192:195], v[204:207], v[114:117]
	v_mfma_f32_16x16x32_bf16 v[102:105], v[184:187], v[208:211], v[102:105]
	v_mfma_f32_16x16x32_bf16 v[98:101], v[192:195], v[208:211], v[98:101]
	v_mfma_f32_16x16x32_bf16 v[86:89], v[184:187], v[220:223], v[86:89]
	v_mfma_f32_16x16x32_bf16 v[82:85], v[192:195], v[220:223], v[82:85]
	v_mfma_f32_16x16x32_bf16 v[70:73], v[184:187], v[224:227], v[70:73]
	v_mfma_f32_16x16x32_bf16 v[66:69], v[192:195], v[224:227], v[66:69]
	s_setprio 0
	s_barrier
	s_add_u32 s52, s38, 0x8000
	s_addc_u32 s53, s39, 0
	s_add_i32 s58, s58, s41
	s_mov_b32 m0, s58
	ds_read_b128 v[196:199], v161 offset:49152
	ds_read_b128 v[200:203], v161 offset:51200
	ds_read_b128 v[204:207], v162 offset:49152
	ds_read_b128 v[208:211], v162 offset:51200
	ds_read_b128 v[212:215], v161 offset:53248
	ds_read_b128 v[216:219], v161 offset:55296
	ds_read_b128 v[220:223], v162 offset:53248
	ds_read_b128 v[224:227], v162 offset:55296
	global_load_lds_dwordx4 v132, s[52:53]
	s_add_i32 m0, s58, 0x2000
	s_add_u32 s38, s38, 0xc000
	v_lshl_add_u64 v[228:229], s[52:53], 0, v[136:137]
	s_addc_u32 s39, s39, 0
	s_add_i32 s52, s59, s41
	global_load_lds_dwordx4 v[228:229], off
	s_mov_b32 m0, s52
	s_nop 0
	global_load_lds_dwordx4 v132, s[38:39]
	s_add_i32 m0, s52, 0x2000
	s_nop 0
	global_load_lds_dwordx4 v136, s[38:39]
	s_mov_b32 m0, s46
	s_nop 0
	global_load_lds_dwordx4 v130, s[36:37]
	s_mov_b32 m0, s47
	s_nop 0
	global_load_lds_dwordx4 v134, s[36:37]
	s_waitcnt vmcnt(8)
	s_waitcnt lgkmcnt(0)
	s_barrier
	s_setprio 1
	v_mfma_f32_16x16x32_bf16 v[62:65], v[146:149], v[196:199], v[62:65]
	v_mfma_f32_16x16x32_bf16 v[58:61], v[172:175], v[196:199], v[58:61]
	v_mfma_f32_16x16x32_bf16 v[46:49], v[146:149], v[200:203], v[46:49]
	v_mfma_f32_16x16x32_bf16 v[42:45], v[172:175], v[200:203], v[42:45]
	v_mfma_f32_16x16x32_bf16 v[30:33], v[146:149], v[212:215], v[30:33]
	v_mfma_f32_16x16x32_bf16 v[26:29], v[172:175], v[212:215], v[26:29]
	v_mfma_f32_16x16x32_bf16 v[14:17], v[146:149], v[216:219], v[14:17]
	v_mfma_f32_16x16x32_bf16 v[10:13], v[172:175], v[216:219], v[10:13]
	v_mfma_f32_16x16x32_bf16 v[62:65], v[168:171], v[204:207], v[62:65]
	v_mfma_f32_16x16x32_bf16 v[58:61], v[176:179], v[204:207], v[58:61]
	v_mfma_f32_16x16x32_bf16 v[46:49], v[168:171], v[208:211], v[46:49]
	v_mfma_f32_16x16x32_bf16 v[42:45], v[176:179], v[208:211], v[42:45]
	v_mfma_f32_16x16x32_bf16 v[30:33], v[168:171], v[220:223], v[30:33]
	v_mfma_f32_16x16x32_bf16 v[26:29], v[176:179], v[220:223], v[26:29]
	v_mfma_f32_16x16x32_bf16 v[14:17], v[168:171], v[224:227], v[14:17]
	v_mfma_f32_16x16x32_bf16 v[10:13], v[176:179], v[224:227], v[10:13]
	s_setprio 0
	s_setprio 1
	v_mfma_f32_16x16x32_bf16 v[54:57], v[180:183], v[196:199], v[54:57]
	v_mfma_f32_16x16x32_bf16 v[50:53], v[188:191], v[196:199], v[50:53]
	v_mfma_f32_16x16x32_bf16 v[38:41], v[180:183], v[200:203], v[38:41]
	v_mfma_f32_16x16x32_bf16 v[34:37], v[188:191], v[200:203], v[34:37]
	v_mfma_f32_16x16x32_bf16 v[22:25], v[180:183], v[212:215], v[22:25]
	v_mfma_f32_16x16x32_bf16 v[18:21], v[188:191], v[212:215], v[18:21]
	v_mfma_f32_16x16x32_bf16 v[6:9], v[180:183], v[216:219], v[6:9]
	v_mfma_f32_16x16x32_bf16 v[2:5], v[188:191], v[216:219], v[2:5]
	v_mfma_f32_16x16x32_bf16 v[54:57], v[184:187], v[204:207], v[54:57]
	v_mfma_f32_16x16x32_bf16 v[50:53], v[192:195], v[204:207], v[50:53]
	v_mfma_f32_16x16x32_bf16 v[38:41], v[184:187], v[208:211], v[38:41]
	v_mfma_f32_16x16x32_bf16 v[34:37], v[192:195], v[208:211], v[34:37]
	v_mfma_f32_16x16x32_bf16 v[22:25], v[184:187], v[220:223], v[22:25]
	v_mfma_f32_16x16x32_bf16 v[18:21], v[192:195], v[220:223], v[18:21]
	v_mfma_f32_16x16x32_bf16 v[6:9], v[184:187], v[224:227], v[6:9]
	v_mfma_f32_16x16x32_bf16 v[2:5], v[192:195], v[224:227], v[2:5]
	s_setprio 0
	s_barrier
	s_add_i32 s57, s57, 2
	s_add_u32 s30, s30, 0x10000
	s_addc_u32 s31, s31, 0
	s_add_u32 s55, s55, 0x10000
	s_addc_u32 s56, s56, 0
	s_cmpk_gt_u32 s57, 0xfd
	s_cbranch_scc0 .LBB0_778
	s_and_b64 vcc, exec, s[16:17]
	s_cbranch_vccz .LBB0_781
	s_barrier
